# as the previous version but rw_rkv transposes back in the prologue (only the layer-1 rg weights stay in a GEMM tail)
# speedup vs baseline: 1.1017x; 1.0011x over previous
; #define TR_LOAD(it_) do { const int kb_ = (it_) / nblk, nb_ = (it_) % nblk; _Pragma("unroll") for (int i = 0; i < 8; ++i) r[i] = *(const f32x4*)(W + (size_t)(kb_ * 64 + 8 * i + (lane >> 3)) * ldw + nb_ * 32 + (lane & 7) * 4); } while (0)
; __device__ __forceinline__ void tr_job(const Ctx& c, int& rot, const float* W, int K, int N, int ldw, bf16_t* WT, int ldt, int row_off) {
;     ...
;     int first = c.gw - (rot % c.ngw); if (first < 0) first += c.ngw;
;     int lane = c.lane; asm volatile("" : "+v"(lane));
;     f32x4 r[8];
;     ...
;     if (first < items) TR_LOAD(first);
; __device__ __forceinline__ void phase_prologue(KP P, const Ctx& c) {
;     ...
;     for (int m = 0; m < 3; ++m) tr_job(c, rot, P->in[I_RWRKV] + (size_t)m * D * D, D, D, D, (bf16_t*)(ws + WS_RW1), D, m * D);
.LBB0_48:
	s_mul_hi_u32 s6, s22, 0x3800
	s_add_u32 s8, s16, 0x7c00000
	s_mul_i32 s6, s6, s21
	s_addc_u32 s9, s17, 0
	s_sub_i32 s6, 0x3800, s6
	s_sub_i32 s7, s6, s21
	s_cmp_ge_u32 s6, s21
	s_cselect_b32 s6, s7, s6
	s_sub_i32 s7, s6, s21
	s_cmp_ge_u32 s6, s21
	s_cselect_b32 s6, s7, s6
	s_load_dwordx2 s[4:5], s[18:19], 0xa0
	s_sub_i32 s6, s20, s6
	s_ashr_i32 s7, s6, 31
	s_and_b32 s7, s7, s14
	s_add_i32 s10, s7, s6
	v_mov_b32_e32 v36, v1
	s_cmpk_lt_i32 s10, 0x800
	s_cbranch_scc0 .LBB0_53
	s_ashr_i32 s6, s10, 31
	s_lshr_b32 s6, s6, 26
	s_add_i32 s6, s10, s6
	s_andn2_b32 s6, s6, 63
	s_sub_i32 s7, s10, s6
	v_ashrrev_i32_e32 v38, 3, v36
	s_waitcnt vmcnt(5)
	v_add_u32_e32 v26, s6, v38
	s_lshl_b32 s6, s7, 5
	s_ashr_i32 s7, s6, 31
	s_lshl_b64 s[6:7], s[6:7], 2
	s_waitcnt lgkmcnt(0)
	s_add_u32 s6, s4, s6
	v_lshlrev_b32_e32 v2, 4, v36
	s_addc_u32 s7, s5, s7
	v_and_b32_e32 v40, 0x70, v2
	v_mov_b32_e32 v41, 0
	v_ashrrev_i32_e32 v27, 31, v26
	v_lshl_add_u64 v[28:29], s[6:7], 0, v[40:41]
	v_lshlrev_b64 v[2:3], 13, v[26:27]
	v_lshl_add_u64 v[10:11], v[28:29], 0, v[2:3]
	v_add_u32_e32 v2, 8, v26
	v_ashrrev_i32_e32 v3, 31, v2
	v_lshlrev_b64 v[2:3], 13, v[2:3]
	v_lshl_add_u64 v[12:13], v[28:29], 0, v[2:3]
	global_load_dwordx4 v[2:5], v[10:11], off nt
	global_load_dwordx4 v[6:9], v[12:13], off nt
	v_add_u32_e32 v10, 16, v26
	v_ashrrev_i32_e32 v11, 31, v10
	v_lshlrev_b64 v[10:11], 13, v[10:11]
	v_lshl_add_u64 v[18:19], v[28:29], 0, v[10:11]
	v_add_u32_e32 v10, 24, v26
	v_ashrrev_i32_e32 v11, 31, v10
	v_lshlrev_b64 v[10:11], 13, v[10:11]
	v_lshl_add_u64 v[20:21], v[28:29], 0, v[10:11]
	global_load_dwordx4 v[10:13], v[18:19], off nt
	global_load_dwordx4 v[14:17], v[20:21], off nt
	v_add_u32_e32 v18, 32, v26
	v_ashrrev_i32_e32 v19, 31, v18
	v_lshlrev_b64 v[18:19], 13, v[18:19]
	s_waitcnt vmcnt(8)
	v_lshl_add_u64 v[30:31], v[28:29], 0, v[18:19]
	v_add_u32_e32 v18, 40, v26
	v_ashrrev_i32_e32 v19, 31, v18
	v_lshlrev_b64 v[18:19], 13, v[18:19]
	v_lshl_add_u64 v[32:33], v[28:29], 0, v[18:19]
	global_load_dwordx4 v[18:21], v[30:31], off nt
	global_load_dwordx4 v[22:25], v[32:33], off nt
	v_add_u32_e32 v30, 48, v26
	v_ashrrev_i32_e32 v31, 31, v30
	v_add_u32_e32 v26, 56, v26
	v_lshlrev_b64 v[30:31], 13, v[30:31]
	v_ashrrev_i32_e32 v27, 31, v26
	v_lshl_add_u64 v[34:35], v[28:29], 0, v[30:31]
	v_lshlrev_b64 v[26:27], 13, v[26:27]
	v_lshl_add_u64 v[42:43], v[28:29], 0, v[26:27]
	global_load_dwordx4 v[26:29], v[34:35], off nt
	global_load_dwordx4 v[30:33], v[42:43], off nt
	v_lshlrev_b32_e32 v36, 3, v36
	v_and_b32_e32 v36, 56, v36
	v_add_u32_e32 v42, s15, v40
	v_lshl_add_u64 v[34:35], s[4:5], 0, v[40:41]
	v_lshlrev_b32_e32 v40, 1, v36
	s_movk_i32 s6, 0x84
	v_mul_u32_u24_e32 v39, 0x84, v36
	v_lshl_add_u64 v[36:37], s[8:9], 0, v[40:41]
	v_lshlrev_b32_e32 v40, 2, v38
	v_add3_u32 v39, s15, v39, v40
	v_mul_lo_u32 v40, v38, s6
	s_lshl_b32 s12, s14, 5
	s_lshl_b32 s11, s10, 5
	v_add_u32_e32 v40, v42, v40
	s_mov_b32 s13, s12
	v_mov_b32_e32 v41, v38
	s_branch .LBB0_51

; #define TR_LOAD(it_) do { const int kb_ = (it_) / nblk, nb_ = (it_) % nblk; _Pragma("unroll") for (int i = 0; i < 8; ++i) r[i] = *(const f32x4*)(W + (size_t)(kb_ * 64 + 8 * i + (lane >> 3)) * ldw + nb_ * 32 + (lane & 7) * 4); } while (0)
; __device__ __forceinline__ void tr_job(const Ctx& c, int& rot, const float* W, int K, int N, int ldw, bf16_t* WT, int ldt, int row_off) {
;     ...
;     int first = c.gw - (rot % c.ngw); if (first < 0) first += c.ngw;
;     int lane = c.lane; asm volatile("" : "+v"(lane));
;     f32x4 r[8];
;     ...
;     if (first < items) TR_LOAD(first);
; __device__ __forceinline__ void phase_prologue(KP P, const Ctx& c) {
;     ...
;     for (int m = 0; m < 3; ++m) tr_job(c, rot, P->in[I_RWRKV] + (size_t)m * D * D, D, D, D, (bf16_t*)(ws + WS_RW1), D, m * D);
.LBB0_53:
	s_lshr_b32 s6, s22, 18
	s_mul_i32 s6, s6, s21
	s_sub_i32 s6, 0x4000, s6
	s_sub_i32 s7, s6, s21
	s_cmp_ge_u32 s6, s21
	s_cselect_b32 s6, s7, s6
	s_sub_i32 s7, s6, s21
	s_cmp_ge_u32 s6, s21
	s_cselect_b32 s6, s7, s6
	s_sub_i32 s6, s20, s6
	s_ashr_i32 s7, s6, 31
	s_and_b32 s7, s7, s14
	s_add_i32 s10, s7, s6
	v_mov_b32_e32 v36, v1
	s_cmpk_gt_i32 s10, 0x7ff
	s_cbranch_scc1 .LBB0_58
	s_waitcnt lgkmcnt(0)
	s_add_u32 s6, s4, 0x1000000
	s_addc_u32 s7, s5, 0
	s_ashr_i32 s11, s10, 31
	s_lshr_b32 s11, s11, 26
	s_add_i32 s11, s10, s11
	s_andn2_b32 s11, s11, 63
	s_sub_i32 s12, s10, s11
	s_lshl_b32 s12, s12, 5
	s_ashr_i32 s13, s12, 31
	v_ashrrev_i32_e32 v38, 3, v36
	s_lshl_b64 s[12:13], s[12:13], 2
	s_waitcnt vmcnt(5)
	v_add_u32_e32 v26, s11, v38
	s_add_u32 s12, s6, s12
	v_lshlrev_b32_e32 v2, 4, v36
	s_addc_u32 s13, s7, s13
	v_and_b32_e32 v40, 0x70, v2
	v_mov_b32_e32 v41, 0
	v_ashrrev_i32_e32 v27, 31, v26
	v_lshl_add_u64 v[28:29], s[12:13], 0, v[40:41]
	v_lshlrev_b64 v[2:3], 13, v[26:27]
	v_lshl_add_u64 v[10:11], v[28:29], 0, v[2:3]
	v_add_u32_e32 v2, 8, v26
	v_ashrrev_i32_e32 v3, 31, v2
	v_lshlrev_b64 v[2:3], 13, v[2:3]
	v_lshl_add_u64 v[12:13], v[28:29], 0, v[2:3]
	global_load_dwordx4 v[2:5], v[10:11], off nt
	global_load_dwordx4 v[6:9], v[12:13], off nt
	v_add_u32_e32 v10, 16, v26
	v_ashrrev_i32_e32 v11, 31, v10
	v_lshlrev_b64 v[10:11], 13, v[10:11]
	v_lshl_add_u64 v[18:19], v[28:29], 0, v[10:11]
	v_add_u32_e32 v10, 24, v26
	v_ashrrev_i32_e32 v11, 31, v10
	v_lshlrev_b64 v[10:11], 13, v[10:11]
	v_lshl_add_u64 v[20:21], v[28:29], 0, v[10:11]
	global_load_dwordx4 v[10:13], v[18:19], off nt
	global_load_dwordx4 v[14:17], v[20:21], off nt
	v_add_u32_e32 v18, 32, v26
	v_ashrrev_i32_e32 v19, 31, v18
	v_lshlrev_b64 v[18:19], 13, v[18:19]
	s_waitcnt vmcnt(8)
	v_lshl_add_u64 v[30:31], v[28:29], 0, v[18:19]
	v_add_u32_e32 v18, 40, v26
	v_ashrrev_i32_e32 v19, 31, v18
	v_lshlrev_b64 v[18:19], 13, v[18:19]
	v_lshl_add_u64 v[32:33], v[28:29], 0, v[18:19]
	global_load_dwordx4 v[18:21], v[30:31], off nt
	global_load_dwordx4 v[22:25], v[32:33], off nt
	v_add_u32_e32 v30, 48, v26
	v_ashrrev_i32_e32 v31, 31, v30
	v_add_u32_e32 v26, 56, v26
	v_lshlrev_b64 v[30:31], 13, v[30:31]
	v_ashrrev_i32_e32 v27, 31, v26
	v_lshl_add_u64 v[34:35], v[28:29], 0, v[30:31]
	v_lshlrev_b64 v[26:27], 13, v[26:27]
	v_lshl_add_u64 v[42:43], v[28:29], 0, v[26:27]
	global_load_dwordx4 v[26:29], v[34:35], off nt
	global_load_dwordx4 v[30:33], v[42:43], off nt
	v_lshlrev_b32_e32 v36, 3, v36
	v_and_b32_e32 v36, 56, v36
	v_add_u32_e32 v42, s15, v40
	v_lshl_add_u64 v[34:35], s[6:7], 0, v[40:41]
	v_lshlrev_b32_e32 v40, 1, v36
	s_movk_i32 s6, 0x84
	v_mul_u32_u24_e32 v39, 0x84, v36
	v_lshl_add_u64 v[36:37], s[8:9], 0, v[40:41]
	v_lshlrev_b32_e32 v40, 2, v38
	v_add3_u32 v39, s15, v39, v40
	v_mul_lo_u32 v40, v38, s6
	s_lshl_b32 s12, s14, 5
	s_lshl_b32 s11, s10, 5
	v_add_u32_e32 v40, v42, v40
	s_mov_b32 s13, s12
	v_mov_b32_e32 v41, v38
	s_branch .LBB0_56

; #define TR_LOAD(it_) do { const int kb_ = (it_) / nblk, nb_ = (it_) % nblk; _Pragma("unroll") for (int i = 0; i < 8; ++i) r[i] = *(const f32x4*)(W + (size_t)(kb_ * 64 + 8 * i + (lane >> 3)) * ldw + nb_ * 32 + (lane & 7) * 4); } while (0)
; __device__ __forceinline__ void tr_job(const Ctx& c, int& rot, const float* W, int K, int N, int ldw, bf16_t* WT, int ldt, int row_off) {
;     ...
;     int first = c.gw - (rot % c.ngw); if (first < 0) first += c.ngw;
;     int lane = c.lane; asm volatile("" : "+v"(lane));
;     f32x4 r[8];
;     ...
;     if (first < items) TR_LOAD(first);
; __device__ __forceinline__ void phase_prologue(KP P, const Ctx& c) {
;     ...
;     for (int m = 0; m < 3; ++m) tr_job(c, rot, P->in[I_RWRKV] + (size_t)m * D * D, D, D, D, (bf16_t*)(ws + WS_RW1), D, m * D);
.LBB0_58:
	s_mul_hi_u32 s6, s22, 0x4800
	s_mul_i32 s6, s6, s21
	s_sub_i32 s6, 0x4800, s6
	s_sub_i32 s7, s6, s21
	s_cmp_ge_u32 s6, s21
	s_cselect_b32 s6, s7, s6
	s_sub_i32 s7, s6, s21
	s_cmp_ge_u32 s6, s21
	s_cselect_b32 s6, s7, s6
	s_sub_i32 s6, s20, s6
	s_ashr_i32 s7, s6, 31
	s_and_b32 s7, s7, s14
	s_add_i32 s6, s7, s6
	v_mov_b32_e32 v36, v1
	s_cmpk_gt_i32 s6, 0x7ff
	s_cbranch_scc1 .LBB0_63
	s_waitcnt lgkmcnt(0)
	s_add_u32 s4, s4, 0x2000000
	s_addc_u32 s5, s5, 0
	s_ashr_i32 s7, s6, 31
	s_lshr_b32 s7, s7, 26
	s_add_i32 s7, s6, s7
	s_andn2_b32 s7, s7, 63
	s_sub_i32 s10, s6, s7
	s_lshl_b32 s10, s10, 5
	s_ashr_i32 s11, s10, 31
	v_ashrrev_i32_e32 v38, 3, v36
	s_lshl_b64 s[10:11], s[10:11], 2
	s_waitcnt vmcnt(5)
	v_add_u32_e32 v26, s7, v38
	s_add_u32 s10, s4, s10
	v_lshlrev_b32_e32 v2, 4, v36
	s_addc_u32 s11, s5, s11
	v_and_b32_e32 v40, 0x70, v2
	v_mov_b32_e32 v41, 0
	v_ashrrev_i32_e32 v27, 31, v26
	v_lshl_add_u64 v[28:29], s[10:11], 0, v[40:41]
	v_lshlrev_b64 v[2:3], 13, v[26:27]
	v_lshl_add_u64 v[10:11], v[28:29], 0, v[2:3]
	v_add_u32_e32 v2, 8, v26
	v_ashrrev_i32_e32 v3, 31, v2
	v_lshlrev_b64 v[2:3], 13, v[2:3]
	v_lshl_add_u64 v[12:13], v[28:29], 0, v[2:3]
	global_load_dwordx4 v[2:5], v[10:11], off nt
	global_load_dwordx4 v[6:9], v[12:13], off nt
	v_add_u32_e32 v10, 16, v26
	v_ashrrev_i32_e32 v11, 31, v10
	v_lshlrev_b64 v[10:11], 13, v[10:11]
	v_lshl_add_u64 v[18:19], v[28:29], 0, v[10:11]
	v_add_u32_e32 v10, 24, v26
	v_ashrrev_i32_e32 v11, 31, v10
	v_lshlrev_b64 v[10:11], 13, v[10:11]
	v_lshl_add_u64 v[20:21], v[28:29], 0, v[10:11]
	global_load_dwordx4 v[10:13], v[18:19], off nt
	global_load_dwordx4 v[14:17], v[20:21], off nt
	v_add_u32_e32 v18, 32, v26
	v_ashrrev_i32_e32 v19, 31, v18
	v_lshlrev_b64 v[18:19], 13, v[18:19]
	s_waitcnt vmcnt(8)
	v_lshl_add_u64 v[30:31], v[28:29], 0, v[18:19]
	v_add_u32_e32 v18, 40, v26
	v_ashrrev_i32_e32 v19, 31, v18
	v_lshlrev_b64 v[18:19], 13, v[18:19]
	v_lshl_add_u64 v[32:33], v[28:29], 0, v[18:19]
	global_load_dwordx4 v[18:21], v[30:31], off nt
	global_load_dwordx4 v[22:25], v[32:33], off nt
	v_add_u32_e32 v30, 48, v26
	v_ashrrev_i32_e32 v31, 31, v30
	v_add_u32_e32 v26, 56, v26
	v_lshlrev_b64 v[30:31], 13, v[30:31]
	v_ashrrev_i32_e32 v27, 31, v26
	v_lshl_add_u64 v[34:35], v[28:29], 0, v[30:31]
	v_lshlrev_b64 v[26:27], 13, v[26:27]
	v_lshl_add_u64 v[42:43], v[28:29], 0, v[26:27]
	global_load_dwordx4 v[26:29], v[34:35], off nt
	global_load_dwordx4 v[30:33], v[42:43], off nt
	v_lshlrev_b32_e32 v36, 3, v36
	v_and_b32_e32 v36, 56, v36
	v_add_u32_e32 v42, s15, v40
	v_lshl_add_u64 v[34:35], s[4:5], 0, v[40:41]
	v_lshlrev_b32_e32 v40, 1, v36
	s_movk_i32 s4, 0x84
	v_mul_u32_u24_e32 v39, 0x84, v36
	v_lshl_add_u64 v[36:37], s[8:9], 0, v[40:41]
	v_lshlrev_b32_e32 v40, 2, v38
	v_add3_u32 v39, s15, v39, v40
	v_mul_lo_u32 v40, v38, s4
	s_lshl_b32 s10, s14, 5
	s_lshl_b32 s7, s6, 5
	v_add_u32_e32 v40, v42, v40
	s_mov_b32 s11, s10
	v_mov_b32_e32 v41, v38
	s_branch .LBB0_61
